# P0 weight conversion loops: counted vmcnt waits (only the tile about to be written to LDS is waited for), padded w_in tile loads like the a_d|b_d tile so every tile issues 4 loads
# baseline (speedup 1.0000x reference)
.LBB0_149:
	s_cmp_lg_u32 s23, 2
	s_cselect_b64 s[26:27], -1, 0
	s_cmp_lt_i32 s37, 44
	s_cselect_b64 s[28:29], -1, 0
	s_or_b64 s[26:27], s[26:27], s[28:29]
	s_cmp_ge_i32 s37, 44
	s_cselect_b64 s[28:29], -1, 0
	s_lshl_b32 s23, s36, 8
	s_and_b64 s[28:29], s[28:29], s[4:5]
	s_or_b32 s25, s23, s3
	s_or_b64 s[26:27], s[26:27], s[28:29]
	v_mov_b32_e32 v2, 0
	v_mov_b32_e32 v6, 0
	v_mov_b32_e32 v7, 0
	v_mov_b32_e32 v8, 0
	v_mov_b32_e32 v9, 0
	s_and_saveexec_b64 s[28:29], s[26:27]
	s_cbranch_execz .LBB0_151
	v_or_b32_e32 v3, s25, v146
	v_mad_i64_i32 v[4:5], s[36:37], s24, v3, 0
	v_lshl_add_u64 v[4:5], v[4:5], 2, s[20:21]
	s_ashr_i32 s23, s22, 31
	v_lshl_add_u64 v[4:5], s[22:23], 2, v[4:5]
	v_lshlrev_b32_e32 v6, 2, v156
	v_mov_b32_e32 v7, 0
	v_lshl_add_u64 v[4:5], v[4:5], 0, v[6:7]
	global_load_dwordx4 v[6:9], v[4:5], off

.LBB0_163:
	s_cmp_lg_u32 s23, 2
	s_cselect_b64 s[26:27], -1, 0
	s_cmp_lt_i32 s37, 44
	s_cselect_b64 s[28:29], -1, 0
	s_or_b64 s[26:27], s[26:27], s[28:29]
	s_cmp_ge_i32 s37, 44
	s_cselect_b64 s[28:29], -1, 0
	s_lshl_b32 s23, s36, 8
	s_and_b64 s[28:29], s[28:29], s[4:5]
	s_or_b32 s25, s23, s3
	s_or_b64 s[26:27], s[26:27], s[28:29]
	v_mov_b32_e32 v22, 0
	v_mov_b32_e32 v18, 0
	v_mov_b32_e32 v19, 0
	v_mov_b32_e32 v20, 0
	v_mov_b32_e32 v21, 0
	s_and_saveexec_b64 s[28:29], s[26:27]
	s_cbranch_execz .LBB0_165
	v_or_b32_e32 v18, s25, v146
	v_mad_i64_i32 v[18:19], s[36:37], s24, v18, 0
	v_lshl_add_u64 v[18:19], v[18:19], 2, s[20:21]
	s_ashr_i32 s23, s22, 31
	v_lshl_add_u64 v[18:19], s[22:23], 2, v[18:19]
	v_lshlrev_b32_e32 v20, 2, v156
	v_mov_b32_e32 v21, 0
	v_lshl_add_u64 v[18:19], v[18:19], 0, v[20:21]
	global_load_dwordx4 v[18:21], v[18:19], off

.LBB0_176:
	s_add_i32 s42, s2, s40
	s_add_i32 s43, s2, s35
	s_add_i32 s41, s44, 2
	s_cmp_ge_i32 s41, s34
	s_cselect_b64 s[18:19], -1, 0
	s_and_b64 vcc, exec, s[18:19]
	s_add_i32 s20, s44, 1
	s_cmp_ge_i32 s20, s34
	s_cbranch_scc1 .Lcv1_w1_drain
	s_cmp_eq_u32 s44, 0
	s_cbranch_scc1 .Lcv1_w1_first
	s_waitcnt vmcnt(8)
	s_branch .Lcv1_w1_go
.Lcv1_w1_first:
	s_waitcnt vmcnt(4)
	s_branch .Lcv1_w1_go

.Lcv1_w1_go:
	ds_write_b128 v149, v[6:9]
	ds_write_b128 v150, v[2:5] offset:8448
	ds_write_b128 v151, v[14:17] offset:16896
	ds_write_b128 v152, v[10:13] offset:25344
	s_cbranch_vccnz .LBB0_190
	s_sub_i32 s20, s42, 64
	s_add_i32 s21, s43, 0xfffff840
	s_cmp_lt_u32 s44, 11
	s_cselect_b32 s23, s20, s21
	s_cmpk_lt_i32 s23, 0xe80
	s_cselect_b32 s20, 0, 0x200
	s_add_i32 s22, s20, s23
	s_cmpk_lt_u32 s22, 0x1640
	s_cselect_b32 s20, 2, 3
	s_cmpk_gt_u32 s22, 0x107f
	s_cselect_b32 s46, s20, 1
	s_cmpk_gt_i32 s22, 0xaff
	s_cselect_b64 s[20:21], -1, 0
	s_and_b64 s[20:21], s[20:21], exec
	s_cselect_b32 s45, s46, 0
	s_cmp_eq_u32 s45, 2
	s_cselect_b64 s[26:27], -1, 0
	s_and_b64 s[20:21], s[26:27], exec
	s_cselect_b32 s24, s36, 0xffffe9c0
	s_cselect_b32 s25, 46, 16
	s_cmpk_gt_i32 s22, 0xaff
	s_cselect_b64 s[20:21], -1, 0
	s_and_b64 s[20:21], s[20:21], exec
	s_cselect_b32 s25, s25, 0x58
	s_add_i32 s20, s22, 0xfffff500
	s_cmpk_lt_u32 s20, 0x580
	s_cselect_b64 s[28:29], -1, 0
	s_and_b64 s[20:21], s[28:29], exec
	s_cselect_b32 s24, 0xfffff500, s24
	s_cmpk_gt_i32 s22, 0xaff
	s_cselect_b64 s[20:21], -1, 0
	s_and_b64 vcc, s[20:21], exec
	s_cselect_b32 s20, s24, 0
	s_abs_i32 s21, s25
	v_cvt_f32_u32_e32 v2, s21
	s_sub_i32 s47, 0, s21
	s_add_i32 s20, s20, s22
	s_ashr_i32 s20, s20, 2
	v_rcp_iflag_f32_e32 v2, v2
	s_abs_i32 s24, s20
	s_xor_b32 s22, s20, s25
	s_ashr_i32 s22, s22, 31
	v_mul_f32_e32 v2, 0x4f7ffffe, v2
	v_cvt_u32_f32_e32 v2, v2
	s_nop 0
	v_readfirstlane_b32 s48, v2
	s_mul_i32 s47, s47, s48
	s_mul_hi_u32 s47, s48, s47
	s_add_i32 s48, s48, s47
	s_mul_hi_u32 s47, s24, s48
	s_mul_i32 s48, s47, s21
	s_sub_i32 s24, s24, s48
	s_add_i32 s48, s47, 1
	s_sub_i32 s49, s24, s21
	s_cmp_ge_u32 s24, s21
	s_cselect_b32 s47, s48, s47
	s_cselect_b32 s24, s49, s24
	s_add_i32 s48, s47, 1
	s_cmp_ge_u32 s24, s21
	s_cselect_b32 s21, s48, s47
	s_xor_b32 s21, s21, s22
	s_sub_i32 s47, s21, s22
	s_mul_i32 s21, s47, s25
	s_sub_i32 s48, s20, s21
	s_mov_b64 s[24:25], -1
	s_cbranch_vccnz .LBB0_179
	s_lshl_b32 s21, s48, 6
	s_and_b32 s21, s21, 0xffffff80
	s_and_b32 s20, s48, 1
	s_add_i32 s22, s21, 0x1600
	s_cmp_eq_u32 s20, 0
	s_cselect_b32 s22, s21, s22
	s_mov_b64 s[24:25], 0
	s_waitcnt lgkmcnt(0)
	s_mov_b64 s[20:21], s[10:11]

.LBB0_181:
	s_cmp_lg_u32 s45, 2
	s_cselect_b64 s[26:27], -1, 0
	s_cmp_lt_i32 s48, 44
	s_cselect_b64 s[28:29], -1, 0
	s_or_b64 s[26:27], s[26:27], s[28:29]
	s_cmp_ge_i32 s48, 44
	s_cselect_b64 s[28:29], -1, 0
	s_lshl_b32 s23, s23, 6
	s_lshl_b32 s25, s47, 8
	s_and_b32 s23, s23, 0xc0
	s_and_b64 s[28:29], s[28:29], s[4:5]
	s_or_b32 s25, s25, s23
	s_or_b64 s[26:27], s[26:27], s[28:29]
	v_mov_b32_e32 v2, 0
	v_mov_b32_e32 v6, 0
	v_mov_b32_e32 v7, 0
	v_mov_b32_e32 v8, 0
	v_mov_b32_e32 v9, 0
	s_and_saveexec_b64 s[28:29], s[26:27]
	s_cbranch_execz .LBB0_183
	v_or_b32_e32 v3, s25, v146
	v_mad_i64_i32 v[4:5], s[46:47], s24, v3, 0
	v_lshl_add_u64 v[4:5], v[4:5], 2, s[20:21]
	s_ashr_i32 s23, s22, 31
	v_lshl_add_u64 v[4:5], s[22:23], 2, v[4:5]
	v_mov_b32_e32 v37, v35
	v_lshl_add_u64 v[4:5], v[4:5], 0, v[36:37]
	global_load_dwordx4 v[6:9], v[4:5], off

.LBB0_190:
	s_add_i32 s20, s42, 0xffffff40
	s_add_i32 s21, s43, 0xfffff640
	s_cmp_lt_u32 s44, 13
	s_cselect_b32 s28, s20, s21
	s_cmpk_lt_i32 s28, 0xe80
	s_cselect_b32 s20, 0, 0x200
	s_add_i32 s29, s20, s28
	s_cmpk_gt_i32 s29, 0xaff
	s_cselect_b64 s[20:21], -1, 0
	s_add_i32 s22, s29, 0xfffff500
	s_cmpk_lt_u32 s22, 0x580
	s_cselect_b64 s[22:23], -1, 0
	s_add_i32 s24, s29, 0xffffef80
	s_cmpk_lt_u32 s24, 0x5c0
	s_cselect_b64 s[24:25], -1, 0
	s_and_b64 s[26:27], s[24:25], exec
	s_cselect_b32 s45, s36, 0xffffe9c0
	s_and_b64 s[26:27], s[22:23], exec
	s_cselect_b32 s45, 0xfffff500, s45
	s_and_b64 s[26:27], s[20:21], exec
	s_cselect_b32 s26, s45, 0
	s_add_i32 s29, s26, s29
	s_and_b64 s[26:27], s[24:25], exec
	s_cselect_b32 s45, 46, 16
	s_and_b64 s[26:27], s[20:21], exec
	s_cselect_b32 s26, s45, 0x58
	s_abs_i32 s27, s26
	v_cvt_f32_u32_e32 v37, s27
	s_sub_i32 s47, 0, s27
	s_ashr_i32 s29, s29, 2
	s_abs_i32 s46, s29
	v_rcp_iflag_f32_e32 v37, v37
	s_ashr_i32 s45, s29, 31
	v_add_u32_e32 v38, 0x400, v154
	v_add_u32_e32 v39, 0x800, v154
	v_mul_f32_e32 v37, 0x4f7ffffe, v37
	v_cvt_u32_f32_e32 v37, v37
	v_add_u32_e32 v41, 0x1000, v154
	s_waitcnt lgkmcnt(0)
	s_barrier
	v_readfirstlane_b32 s48, v37
	s_mul_i32 s47, s47, s48
	s_mul_hi_u32 s47, s48, s47
	s_add_i32 s48, s48, s47
	s_mul_hi_u32 s47, s46, s48
	s_mul_i32 s48, s47, s27
	s_sub_i32 s46, s46, s48
	s_add_i32 s48, s47, 1
	s_sub_i32 s49, s46, s27
	s_cmp_ge_u32 s46, s27
	s_cselect_b32 s47, s48, s47
	s_cselect_b32 s46, s49, s46
	s_add_i32 s48, s47, 1
	s_cmp_ge_u32 s46, s27
	s_cselect_b32 s27, s48, s47
	s_xor_b32 s27, s27, s45
	s_sub_i32 s27, s27, s45
	s_mul_i32 s26, s27, s26
	s_sub_i32 s26, s29, s26
	s_and_b64 s[24:25], s[24:25], exec
	s_cselect_b32 s29, s39, 0x5900000
	s_and_b64 s[24:25], s[22:23], exec
	s_cselect_b32 s24, 0x2c00000, s29
	s_and_b64 s[20:21], s[20:21], exec
	s_cselect_b32 s21, s24, 0
	s_lshl_b32 s24, s28, 6
	ds_read2_b32 v[46:47], v154 offset1:132
	ds_read2_b32 v[48:49], v38 offset0:8 offset1:140
	ds_read2_b32 v[50:51], v39 offset0:16 offset1:148
	ds_read2_b32 v[54:55], v41 offset0:32 offset1:164
	s_lshl_b32 s20, s27, 8
	s_and_b32 s24, s24, 0xc0
	s_or_b32 s20, s20, s24
	v_add_u32_e32 v40, 0xc00, v154
	s_and_b64 s[22:23], s[22:23], exec
	ds_read2_b32 v[52:53], v40 offset0:24 offset1:156
	v_add_u32_e32 v42, 0x1400, v154
	v_add_u32_e32 v43, 0x1800, v154
	v_add_u32_e32 v44, 0x1c00, v154
	s_cselect_b32 s24, 0x1600, s37
	s_add_u32 s22, s14, s21
	ds_read2_b32 v[56:57], v42 offset0:40 offset1:172
	ds_read2_b32 v[58:59], v43 offset0:48 offset1:180
	ds_read2_b32 v[60:61], v44 offset0:56 offset1:188
	v_lshl_add_u32 v37, s26, 7, v153
	s_addc_u32 s23, s15, 0
	s_waitcnt lgkmcnt(7)
	v_cvt_pk_bf16_f32 v46, v46, v47
	s_waitcnt lgkmcnt(6)
	v_cvt_pk_bf16_f32 v47, v48, v49
	s_waitcnt lgkmcnt(5)
	v_cvt_pk_bf16_f32 v48, v50, v51
	s_waitcnt lgkmcnt(4)
	v_cvt_pk_bf16_f32 v50, v54, v55
	v_mad_i64_i32 v[54:55], s[24:25], s24, v37, 0
	v_lshl_add_u64 v[54:55], v[54:55], 1, s[22:23]
	s_ashr_i32 s21, s20, 31
	v_lshl_add_u64 v[54:55], s[20:21], 1, v[54:55]
	s_add_i32 s45, s44, 1
	s_waitcnt lgkmcnt(3)
	v_cvt_pk_bf16_f32 v49, v52, v53
	v_lshl_add_u64 v[54:55], v[54:55], 0, v[34:35]
	s_cmp_ge_i32 s45, s34
	s_waitcnt lgkmcnt(2)
	v_cvt_pk_bf16_f32 v51, v56, v57
	s_waitcnt lgkmcnt(1)
	v_cvt_pk_bf16_f32 v52, v58, v59
	s_waitcnt lgkmcnt(0)
	v_cvt_pk_bf16_f32 v53, v60, v61
	global_store_dwordx4 v[54:55], v[46:49], off
	global_store_dwordx4 v[54:55], v[50:53], off offset:16
	s_barrier
	s_cbranch_scc1 .LBB0_175
	s_cmp_ge_i32 s41, s34
	s_cbranch_scc1 .Lcv1_w2_drain
	s_cmp_eq_u32 s44, 0
	s_cbranch_scc1 .Lcv1_w2_first
	s_waitcnt vmcnt(8)
	s_branch .Lcv1_w2_go
.Lcv1_w2_first:
	s_waitcnt vmcnt(6)
	s_branch .Lcv1_w2_go

.Lcv1_w2_go:
	s_add_i32 s20, s44, 3
	s_cmp_ge_i32 s20, s34
	ds_write_b128 v149, v[18:21]
	ds_write_b128 v150, v[22:25] offset:8448
	ds_write_b128 v151, v[26:29] offset:16896
	ds_write_b128 v152, v[30:33] offset:25344
	s_cbranch_scc1 .LBB0_174
	s_add_i32 s20, s43, 0xfffff940
	s_cmp_lt_u32 s44, 10
	s_cselect_b32 s23, s42, s20
	s_cmpk_lt_i32 s23, 0xe80
	s_cselect_b32 s20, 0, 0x200
	s_add_i32 s22, s20, s23
	s_cmpk_lt_u32 s22, 0x1640
	s_cselect_b32 s20, 2, 3
	s_cmpk_gt_u32 s22, 0x107f
	s_cselect_b32 s46, s20, 1
	s_cmpk_gt_i32 s22, 0xaff
	s_cselect_b64 s[20:21], -1, 0
	s_and_b64 s[20:21], s[20:21], exec
	s_cselect_b32 s44, s46, 0
	s_cmp_eq_u32 s44, 2
	s_cselect_b64 s[26:27], -1, 0
	s_and_b64 s[20:21], s[26:27], exec
	s_cselect_b32 s24, s36, 0xffffe9c0
	s_cselect_b32 s25, 46, 16
	s_cmpk_gt_i32 s22, 0xaff
	s_cselect_b64 s[20:21], -1, 0
	s_and_b64 s[20:21], s[20:21], exec
	s_cselect_b32 s25, s25, 0x58
	s_add_i32 s20, s22, 0xfffff500
	s_cmpk_lt_u32 s20, 0x580
	s_cselect_b64 s[28:29], -1, 0
	s_and_b64 s[20:21], s[28:29], exec
	s_cselect_b32 s24, 0xfffff500, s24
	s_cmpk_gt_i32 s22, 0xaff
	s_cselect_b64 s[20:21], -1, 0
	s_and_b64 vcc, s[20:21], exec
	s_cselect_b32 s20, s24, 0
	s_abs_i32 s21, s25
	v_cvt_f32_u32_e32 v18, s21
	s_sub_i32 s47, 0, s21
	s_add_i32 s20, s20, s22
	s_ashr_i32 s20, s20, 2
	v_rcp_iflag_f32_e32 v18, v18
	s_abs_i32 s24, s20
	s_xor_b32 s22, s20, s25
	s_ashr_i32 s22, s22, 31
	v_mul_f32_e32 v18, 0x4f7ffffe, v18
	v_cvt_u32_f32_e32 v18, v18
	s_nop 0
	v_readfirstlane_b32 s48, v18
	s_mul_i32 s47, s47, s48
	s_mul_hi_u32 s47, s48, s47
	s_add_i32 s48, s48, s47
	s_mul_hi_u32 s47, s24, s48
	s_mul_i32 s48, s47, s21
	s_sub_i32 s24, s24, s48
	s_add_i32 s48, s47, 1
	s_sub_i32 s49, s24, s21
	s_cmp_ge_u32 s24, s21
	s_cselect_b32 s47, s48, s47
	s_cselect_b32 s24, s49, s24
	s_add_i32 s48, s47, 1
	s_cmp_ge_u32 s24, s21
	s_cselect_b32 s21, s48, s47
	s_xor_b32 s21, s21, s22
	s_sub_i32 s47, s21, s22
	s_mul_i32 s21, s47, s25
	s_sub_i32 s48, s20, s21
	s_mov_b64 s[24:25], -1
	s_cbranch_vccnz .LBB0_194
	s_lshl_b32 s21, s48, 6
	s_and_b32 s21, s21, 0xffffff80
	s_and_b32 s20, s48, 1
	s_add_i32 s22, s21, 0x1600
	s_cmp_eq_u32 s20, 0
	s_cselect_b32 s22, s21, s22
	s_mov_b64 s[24:25], 0
	s_mov_b64 s[20:21], s[10:11]

.LBB0_196:
	s_cmp_lg_u32 s44, 2
	s_cselect_b64 s[26:27], -1, 0
	s_cmp_lt_i32 s48, 44
	s_cselect_b64 s[28:29], -1, 0
	s_or_b64 s[26:27], s[26:27], s[28:29]
	s_cmp_ge_i32 s48, 44
	s_cselect_b64 s[28:29], -1, 0
	s_lshl_b32 s23, s23, 6
	s_lshl_b32 s25, s47, 8
	s_and_b32 s23, s23, 0xc0
	s_and_b64 s[28:29], s[28:29], s[4:5]
	s_or_b32 s25, s25, s23
	s_or_b64 s[26:27], s[26:27], s[28:29]
	v_mov_b32_e32 v22, 0
	v_mov_b32_e32 v18, 0
	v_mov_b32_e32 v19, 0
	v_mov_b32_e32 v20, 0
	v_mov_b32_e32 v21, 0
	s_and_saveexec_b64 s[28:29], s[26:27]
	s_cbranch_execz .LBB0_198
	v_or_b32_e32 v18, s25, v146
	v_mad_i64_i32 v[18:19], s[46:47], s24, v18, 0
	v_lshl_add_u64 v[18:19], v[18:19], 2, s[20:21]
	s_ashr_i32 s23, s22, 31
	v_lshl_add_u64 v[18:19], s[22:23], 2, v[18:19]
	v_mov_b32_e32 v37, v35
	v_lshl_add_u64 v[18:19], v[18:19], 0, v[36:37]
	global_load_dwordx4 v[18:21], v[18:19], off

.LBB0_215:
	s_add_i32 s37, s29, -2
	s_cmp_ge_i32 s37, s30
	s_cbranch_scc1 .Lcv2_w1_drain
	s_cmp_eq_u32 s29, 3
	s_cbranch_scc1 .Lcv2_w1_first
	s_waitcnt vmcnt(8)
	s_branch .Lcv2_w1_go

.Lcv2_w1_go:
	s_add_i32 s37, s29, -1
	s_cmp_ge_i32 s37, s30
	ds_write_b128 v149, v[2:5]
	ds_write_b128 v150, v[6:9] offset:8448
	ds_write_b128 v151, v[10:13] offset:16896
	ds_write_b128 v152, v[14:17] offset:25344
	s_cbranch_scc1 .LBB0_229
	s_add_i32 s20, s28, 0xffffff00
	s_cmpk_lt_i32 s20, 0xe80
	s_cselect_b32 s22, 0, 0x200
	s_add_i32 s23, s22, s28
	s_add_i32 s39, s23, 0xffffff00
	s_cmpk_lt_u32 s39, 0x1640
	s_cselect_b32 s18, 2, 3
	s_cmpk_gt_u32 s39, 0x107f
	s_cselect_b32 s38, s18, 1
	s_cmpk_gt_i32 s39, 0xaff
	s_cselect_b64 s[18:19], -1, 0
	s_and_b64 s[18:19], s[18:19], exec
	s_cselect_b32 s21, s38, 0
	s_cmp_eq_u32 s21, 2
	s_cselect_b64 s[24:25], -1, 0
	s_and_b64 s[18:19], s[24:25], exec
	s_cselect_b32 s40, s31, 0xffffe9c0
	s_cselect_b32 s26, 46, 16
	s_cmpk_gt_i32 s39, 0xaff
	s_cselect_b64 s[18:19], -1, 0
	s_and_b64 s[18:19], s[18:19], exec
	s_cselect_b32 s41, s26, 0x58
	s_addk_i32 s23, 0xf400
	s_cmpk_lt_u32 s23, 0x580
	s_cselect_b64 s[26:27], -1, 0
	s_and_b64 s[18:19], s[26:27], exec
	s_cselect_b32 s23, 0xfffff500, s40
	s_cmpk_gt_i32 s39, 0xaff
	s_cselect_b64 s[18:19], -1, 0
	s_and_b64 vcc, s[18:19], exec
	s_cselect_b32 s18, s23, 0
	s_abs_i32 s19, s41
	v_cvt_f32_u32_e32 v2, s19
	s_add_i32 s18, s18, s22
	s_sub_i32 s23, 0, s19
	s_add_i32 s20, s20, s18
	v_rcp_iflag_f32_e32 v2, v2
	s_ashr_i32 s18, s20, 2
	s_abs_i32 s22, s18
	s_xor_b32 s20, s18, s41
	v_mul_f32_e32 v2, 0x4f7ffffe, v2
	v_cvt_u32_f32_e32 v2, v2
	s_ashr_i32 s20, s20, 31
	v_readfirstlane_b32 s39, v2
	s_mul_i32 s23, s23, s39
	s_mul_hi_u32 s23, s39, s23
	s_add_i32 s39, s39, s23
	s_mul_hi_u32 s23, s22, s39
	s_mul_i32 s39, s23, s19
	s_sub_i32 s22, s22, s39
	s_add_i32 s39, s23, 1
	s_sub_i32 s40, s22, s19
	s_cmp_ge_u32 s22, s19
	s_cselect_b32 s23, s39, s23
	s_cselect_b32 s22, s40, s22
	s_add_i32 s39, s23, 1
	s_cmp_ge_u32 s22, s19
	s_cselect_b32 s19, s39, s23
	s_xor_b32 s19, s19, s20
	s_sub_i32 s39, s19, s20
	s_mul_i32 s19, s39, s41
	s_sub_i32 s40, s18, s19
	s_mov_b64 s[22:23], -1
	s_cbranch_vccnz .LBB0_218
	s_lshl_b32 s19, s40, 6
	s_and_b32 s19, s19, 0xffffff80
	s_and_b32 s18, s40, 1
	s_add_i32 s20, s19, 0x1600
	s_cmp_eq_u32 s18, 0
	s_cselect_b32 s20, s19, s20
	s_mov_b64 s[22:23], 0
	s_waitcnt lgkmcnt(0)
	s_mov_b64 s[18:19], s[10:11]

.LBB0_220:
	s_cmp_lg_u32 s21, 2
	s_cselect_b64 s[24:25], -1, 0
	s_cmp_lt_i32 s40, 44
	s_cselect_b64 s[26:27], -1, 0
	s_or_b64 s[24:25], s[24:25], s[26:27]
	s_cmp_ge_i32 s40, 44
	s_cselect_b64 s[26:27], -1, 0
	s_lshl_b32 s21, s39, 8
	s_and_b64 s[26:27], s[26:27], s[4:5]
	s_or_b32 s23, s21, s3
	s_or_b64 s[24:25], s[24:25], s[26:27]
	v_mov_b32_e32 v6, 0
	v_mov_b32_e32 v2, 0
	v_mov_b32_e32 v3, 0
	v_mov_b32_e32 v4, 0
	v_mov_b32_e32 v5, 0
	s_and_saveexec_b64 s[26:27], s[24:25]
	s_cbranch_execz .LBB0_222
	v_or_b32_e32 v2, s23, v146
	v_mad_i64_i32 v[2:3], s[38:39], s22, v2, 0
	v_lshl_add_u64 v[2:3], v[2:3], 2, s[18:19]
	s_ashr_i32 s21, s20, 31
	v_lshl_add_u64 v[2:3], s[20:21], 2, v[2:3]
	v_mov_b32_e32 v37, v35
	v_lshl_add_u64 v[2:3], v[2:3], 0, v[36:37]
	global_load_dwordx4 v[2:5], v[2:3], off

.LBB0_229:
	s_add_i32 s26, s28, 0xfffffd00
	s_cmpk_lt_i32 s26, 0xe80
	s_cselect_b32 s27, 0, 0x200
	s_add_i32 s22, s27, s28
	s_add_i32 s18, s22, 0xfffffd00
	s_cmpk_gt_i32 s18, 0xaff
	s_cselect_b64 s[18:19], -1, 0
	s_add_i32 s20, s22, 0xfffff200
	s_cmpk_lt_u32 s20, 0x580
	s_cselect_b64 s[20:21], -1, 0
	s_addk_i32 s22, 0xec80
	s_cmpk_lt_u32 s22, 0x5c0
	s_cselect_b64 s[22:23], -1, 0
	s_and_b64 s[24:25], s[22:23], exec
	s_cselect_b32 s38, s31, 0xffffe9c0
	s_and_b64 s[24:25], s[20:21], exec
	s_cselect_b32 s38, 0xfffff500, s38
	s_and_b64 s[24:25], s[18:19], exec
	s_cselect_b32 s24, s38, 0
	s_add_i32 s24, s24, s27
	s_add_i32 s26, s26, s24
	s_and_b64 s[24:25], s[22:23], exec
	s_cselect_b32 s27, 46, 16
	s_and_b64 s[24:25], s[18:19], exec
	s_cselect_b32 s24, s27, 0x58
	s_abs_i32 s25, s24
	v_cvt_f32_u32_e32 v37, s25
	s_sub_i32 s39, 0, s25
	s_ashr_i32 s26, s26, 2
	s_abs_i32 s38, s26
	v_rcp_iflag_f32_e32 v37, v37
	s_ashr_i32 s27, s26, 31
	v_add_u32_e32 v38, 0x400, v154
	v_add_u32_e32 v39, 0x800, v154
	v_mul_f32_e32 v37, 0x4f7ffffe, v37
	v_cvt_u32_f32_e32 v37, v37
	v_add_u32_e32 v41, 0x1000, v154
	s_waitcnt lgkmcnt(0)
	s_barrier
	v_readfirstlane_b32 s40, v37
	s_mul_i32 s39, s39, s40
	s_mul_hi_u32 s39, s40, s39
	s_add_i32 s40, s40, s39
	s_mul_hi_u32 s39, s38, s40
	s_mul_i32 s40, s39, s25
	s_sub_i32 s38, s38, s40
	s_add_i32 s40, s39, 1
	s_sub_i32 s41, s38, s25
	s_cmp_ge_u32 s38, s25
	s_cselect_b32 s39, s40, s39
	s_cselect_b32 s38, s41, s38
	s_add_i32 s40, s39, 1
	s_cmp_ge_u32 s38, s25
	s_cselect_b32 s25, s40, s39
	s_xor_b32 s25, s25, s27
	s_sub_i32 s25, s25, s27
	s_mul_i32 s24, s25, s24
	s_sub_i32 s24, s26, s24
	s_and_b64 s[22:23], s[22:23], exec
	s_cselect_b32 s26, s36, 0x5900000
	s_and_b64 s[22:23], s[20:21], exec
	s_cselect_b32 s22, 0x2c00000, s26
	s_and_b64 s[18:19], s[18:19], exec
	ds_read2_b32 v[46:47], v154 offset1:132
	ds_read2_b32 v[48:49], v38 offset0:8 offset1:140
	ds_read2_b32 v[50:51], v39 offset0:16 offset1:148
	ds_read2_b32 v[54:55], v41 offset0:32 offset1:164
	s_cselect_b32 s19, s22, 0
	s_lshl_b32 s18, s25, 8
	s_or_b32 s18, s18, s3
	v_add_u32_e32 v40, 0xc00, v154
	s_and_b64 s[20:21], s[20:21], exec
	ds_read2_b32 v[52:53], v40 offset0:24 offset1:156
	v_add_u32_e32 v42, 0x1400, v154
	v_add_u32_e32 v43, 0x1800, v154
	v_add_u32_e32 v44, 0x1c00, v154
	s_cselect_b32 s22, 0x1600, s34
	s_add_u32 s20, s14, s19
	ds_read2_b32 v[56:57], v42 offset0:40 offset1:172
	ds_read2_b32 v[58:59], v43 offset0:48 offset1:180
	ds_read2_b32 v[60:61], v44 offset0:56 offset1:188
	v_lshl_add_u32 v37, s24, 7, v153
	s_addc_u32 s21, s15, 0
	s_waitcnt lgkmcnt(7)
	v_cvt_pk_bf16_f32 v46, v46, v47
	s_waitcnt lgkmcnt(6)
	v_cvt_pk_bf16_f32 v47, v48, v49
	s_waitcnt lgkmcnt(5)
	v_cvt_pk_bf16_f32 v48, v50, v51
	s_waitcnt lgkmcnt(4)
	v_cvt_pk_bf16_f32 v50, v54, v55
	v_mad_i64_i32 v[54:55], s[22:23], s22, v37, 0
	v_lshl_add_u64 v[54:55], v[54:55], 1, s[20:21]
	s_ashr_i32 s19, s18, 31
	v_lshl_add_u64 v[54:55], s[18:19], 1, v[54:55]
	s_add_i32 s18, s29, -2
	s_waitcnt lgkmcnt(3)
	v_cvt_pk_bf16_f32 v49, v52, v53
	v_lshl_add_u64 v[54:55], v[54:55], 0, v[34:35]
	s_cmp_ge_i32 s18, s30
	s_waitcnt lgkmcnt(2)
	v_cvt_pk_bf16_f32 v51, v56, v57
	s_waitcnt lgkmcnt(1)
	v_cvt_pk_bf16_f32 v52, v58, v59
	s_waitcnt lgkmcnt(0)
	v_cvt_pk_bf16_f32 v53, v60, v61
	global_store_dwordx4 v[54:55], v[46:49], off
	global_store_dwordx4 v[54:55], v[50:53], off offset:16
	s_barrier
	s_cbranch_scc1 .LBB0_214
	s_add_i32 s18, s29, -1
	s_cmp_ge_i32 s18, s30
	s_cbranch_scc1 .Lcv2_w2_drain
	s_cmp_eq_u32 s29, 3
	s_cbranch_scc1 .Lcv2_w2_first
	s_waitcnt vmcnt(8)
	s_branch .Lcv2_w2_go

.Lcv2_w2_go:
	s_cmp_ge_i32 s29, s30
	ds_write_b128 v149, v[18:21]
	ds_write_b128 v150, v[22:25] offset:8448
	ds_write_b128 v151, v[26:29] offset:16896
	ds_write_b128 v152, v[30:33] offset:25344
	s_cbranch_scc1 .LBB0_213
	s_cmpk_lt_i32 s28, 0xe80
	s_cselect_b32 s18, 0, 0x200
	s_add_i32 s20, s18, s28
	s_cmpk_lt_u32 s20, 0x1640
	s_cselect_b32 s18, 2, 3
	s_cmpk_gt_u32 s20, 0x107f
	s_cselect_b32 s38, s18, 1
	s_cmpk_gt_i32 s20, 0xaff
	s_cselect_b64 s[18:19], -1, 0
	s_and_b64 s[18:19], s[18:19], exec
	s_cselect_b32 s21, s38, 0
	s_cmp_eq_u32 s21, 2
	s_cselect_b64 s[24:25], -1, 0
	s_and_b64 s[18:19], s[24:25], exec
	s_cselect_b32 s22, s31, 0xffffe9c0
	s_cselect_b32 s23, 46, 16
	s_cmpk_gt_i32 s20, 0xaff
	s_cselect_b64 s[18:19], -1, 0
	s_and_b64 s[18:19], s[18:19], exec
	s_cselect_b32 s23, s23, 0x58
	s_add_i32 s18, s20, 0xfffff500
	s_cmpk_lt_u32 s18, 0x580
	s_cselect_b64 s[26:27], -1, 0
	s_and_b64 s[18:19], s[26:27], exec
	s_cselect_b32 s22, 0xfffff500, s22
	s_cmpk_gt_i32 s20, 0xaff
	s_cselect_b64 s[18:19], -1, 0
	s_and_b64 vcc, s[18:19], exec
	s_cselect_b32 s18, s22, 0
	s_abs_i32 s19, s23
	v_cvt_f32_u32_e32 v18, s19
	s_sub_i32 s39, 0, s19
	s_add_i32 s20, s20, s18
	s_ashr_i32 s18, s20, 2
	v_rcp_iflag_f32_e32 v18, v18
	s_abs_i32 s22, s18
	s_xor_b32 s20, s18, s23
	s_ashr_i32 s20, s20, 31
	v_mul_f32_e32 v18, 0x4f7ffffe, v18
	v_cvt_u32_f32_e32 v18, v18
	s_nop 0
	v_readfirstlane_b32 s40, v18
	s_mul_i32 s39, s39, s40
	s_mul_hi_u32 s39, s40, s39
	s_add_i32 s40, s40, s39
	s_mul_hi_u32 s39, s22, s40
	s_mul_i32 s40, s39, s19
	s_sub_i32 s22, s22, s40
	s_add_i32 s40, s39, 1
	s_sub_i32 s41, s22, s19
	s_cmp_ge_u32 s22, s19
	s_cselect_b32 s39, s40, s39
	s_cselect_b32 s22, s41, s22
	s_add_i32 s40, s39, 1
	s_cmp_ge_u32 s22, s19
	s_cselect_b32 s19, s40, s39
	s_xor_b32 s19, s19, s20
	s_sub_i32 s39, s19, s20
	s_mul_i32 s19, s39, s23
	s_sub_i32 s40, s18, s19
	s_mov_b64 s[22:23], -1
	s_cbranch_vccnz .LBB0_233
	s_lshl_b32 s19, s40, 6
	s_and_b32 s19, s19, 0xffffff80
	s_and_b32 s18, s40, 1
	s_add_i32 s20, s19, 0x1600
	s_cmp_eq_u32 s18, 0
	s_cselect_b32 s20, s19, s20
	s_mov_b64 s[22:23], 0
	s_mov_b64 s[18:19], s[10:11]

.LBB0_235:
	s_cmp_lg_u32 s21, 2
	s_cselect_b64 s[24:25], -1, 0
	s_cmp_lt_i32 s40, 44
	s_cselect_b64 s[26:27], -1, 0
	s_or_b64 s[24:25], s[24:25], s[26:27]
	s_cmp_ge_i32 s40, 44
	s_cselect_b64 s[26:27], -1, 0
	s_lshl_b32 s21, s39, 8
	s_and_b64 s[26:27], s[26:27], s[4:5]
	s_or_b32 s23, s21, s3
	s_or_b64 s[24:25], s[24:25], s[26:27]
	v_mov_b32_e32 v22, 0
	v_mov_b32_e32 v18, 0
	v_mov_b32_e32 v19, 0
	v_mov_b32_e32 v20, 0
	v_mov_b32_e32 v21, 0
	s_and_saveexec_b64 s[26:27], s[24:25]
	s_cbranch_execz .LBB0_237
	v_or_b32_e32 v18, s23, v146
	v_mad_i64_i32 v[18:19], s[38:39], s22, v18, 0
	v_lshl_add_u64 v[18:19], v[18:19], 2, s[18:19]
	s_ashr_i32 s21, s20, 31
	v_lshl_add_u64 v[18:19], s[20:21], 2, v[18:19]
	v_mov_b32_e32 v37, v35
	v_lshl_add_u64 v[18:19], v[18:19], 0, v[36:37]
	global_load_dwordx4 v[18:21], v[18:19], off
